# scan pass 2 rewritten: next chunk P rows prefetched one chunk ahead into a second register set, v_readlane broadcast instead of ds_bpermute (on top of v6)
# speedup vs baseline: 1.0233x; 1.0088x over previous
; __device__ __forceinline__ void scan_pass2(const Ctx&, unsigned char* ws) { const Ctx c = mk_ctx();
;     float* PL = (float*)(ws + WS_R + R_PL); const int lane = c.lane;
;     const int xcd_ = blockIdx.x & 7, tt_ = (blockIdx.x >> 3) * 8 + c.wid;
;     for (int task = (gridDim.x == 256) ? ((tt_ < 128) ? ((xcd_ + 8 * (tt_ >> 6)) * 64 + (tt_ & 63)) : 16 * 64) : c.gw; task < 16 * 64; task += (gridDim.x == 256) ? 16 * 64 : c.NGW) { const int chain = task >> 6, i = task & 63;
;         float s = 0.f;
;         for (int cc = 0; cc < NCH - 1; ++cc) { float* P = PL + (((size_t)chain * NCH + cc) * 2) * 4096; float* L = P + 4096 + i * 64;
;             float a0 = L[lane], a1 = 0.f, a2 = 0.f, a3 = 0.f;
.LBB0_2031:
	s_lshl_b32 s0, s5, 2
	s_and_b32 s6, s0, 0x3f00
	s_ashr_i32 s0, s4, 6
	s_ashr_i32 s1, s0, 31
	s_lshl_b64 s[0:1], s[0:1], 21
	s_or_b32 s6, s0, s6
	s_mov_b32 s7, s1
	v_lshl_add_u64 v[6:7], v[4:5], 0, s[6:7]
	v_lshl_add_u64 v[8:9], v[2:3], 0, s[0:1]
	v_mov_b32_e32 v159, 0
	v_add_co_u32_e32 v160, vcc, 0x7c00000, v8
	s_nop 1
	v_addc_co_u32_e32 v161, vcc, 0, v9, vcc
	v_add_co_u32_e32 v162, vcc, 0x1000, v160
	s_nop 1
	v_addc_co_u32_e32 v163, vcc, 0, v161, vcc
	v_add_co_u32_e32 v164, vcc, 0x2000, v160
	s_nop 1
	v_addc_co_u32_e32 v165, vcc, 0, v161, vcc
	v_add_co_u32_e32 v166, vcc, 0x3000, v160
	s_nop 1
	v_addc_co_u32_e32 v167, vcc, 0, v161, vcc
	s_mov_b64 s[0:1], 0x8000
	v_mov_b32_e32 v170, 0
	global_load_dword v12, v[6:7], off
	global_load_dword v16, v[160:161], off
	global_load_dword v17, v[160:161], off offset:256
	global_load_dword v18, v[160:161], off offset:512
	global_load_dword v19, v[160:161], off offset:768
	global_load_dword v20, v[160:161], off offset:1024
	global_load_dword v21, v[160:161], off offset:1280
	global_load_dword v22, v[160:161], off offset:1536
	global_load_dword v23, v[160:161], off offset:1792
	global_load_dword v24, v[160:161], off offset:2048
	global_load_dword v25, v[160:161], off offset:2304
	global_load_dword v26, v[160:161], off offset:2560
	global_load_dword v27, v[160:161], off offset:2816
	global_load_dword v28, v[160:161], off offset:3072
	global_load_dword v29, v[160:161], off offset:3328
	global_load_dword v30, v[160:161], off offset:3584
	global_load_dword v31, v[160:161], off offset:3840
	global_load_dword v32, v[162:163], off
	global_load_dword v33, v[162:163], off offset:256
	global_load_dword v34, v[162:163], off offset:512
	global_load_dword v35, v[162:163], off offset:768
	global_load_dword v36, v[162:163], off offset:1024
	global_load_dword v37, v[162:163], off offset:1280
	global_load_dword v38, v[162:163], off offset:1536
	global_load_dword v39, v[162:163], off offset:1792
	global_load_dword v40, v[162:163], off offset:2048
	global_load_dword v41, v[162:163], off offset:2304
	global_load_dword v42, v[162:163], off offset:2560
	global_load_dword v43, v[162:163], off offset:2816
	global_load_dword v44, v[162:163], off offset:3072
	global_load_dword v45, v[162:163], off offset:3328
	global_load_dword v46, v[162:163], off offset:3584
	global_load_dword v47, v[162:163], off offset:3840
	global_load_dword v48, v[164:165], off
	global_load_dword v49, v[164:165], off offset:256
	global_load_dword v50, v[164:165], off offset:512
	global_load_dword v51, v[164:165], off offset:768
	global_load_dword v52, v[164:165], off offset:1024
	global_load_dword v53, v[164:165], off offset:1280
	global_load_dword v54, v[164:165], off offset:1536
	global_load_dword v55, v[164:165], off offset:1792
	global_load_dword v56, v[164:165], off offset:2048
	global_load_dword v57, v[164:165], off offset:2304
	global_load_dword v58, v[164:165], off offset:2560
	global_load_dword v59, v[164:165], off offset:2816
	global_load_dword v60, v[164:165], off offset:3072
	global_load_dword v61, v[164:165], off offset:3328
	global_load_dword v62, v[164:165], off offset:3584
	global_load_dword v63, v[164:165], off offset:3840
	global_load_dword v64, v[166:167], off
	global_load_dword v65, v[166:167], off offset:256
	global_load_dword v66, v[166:167], off offset:512
	global_load_dword v67, v[166:167], off offset:768
	global_load_dword v68, v[166:167], off offset:1024
	global_load_dword v69, v[166:167], off offset:1280
	global_load_dword v70, v[166:167], off offset:1536
	global_load_dword v71, v[166:167], off offset:1792
	global_load_dword v72, v[166:167], off offset:2048
	global_load_dword v73, v[166:167], off offset:2304
	global_load_dword v74, v[166:167], off offset:2560
	global_load_dword v75, v[166:167], off offset:2816
	global_load_dword v76, v[166:167], off offset:3072
	global_load_dword v77, v[166:167], off offset:3328
	global_load_dword v78, v[166:167], off offset:3584
	global_load_dword v79, v[166:167], off offset:3840
	v_lshl_add_u64 v[160:161], v[160:161], 0, s[0:1]
	v_lshl_add_u64 v[162:163], v[162:163], 0, s[0:1]
	v_lshl_add_u64 v[164:165], v[164:165], 0, s[0:1]
	v_lshl_add_u64 v[166:167], v[166:167], 0, s[0:1]
	s_waitcnt vmcnt(0)
; __device__ __forceinline__ void scan_pass2(const Ctx&, unsigned char* ws) { const Ctx c = mk_ctx();
;     ...
;         for (int cc = 0; cc < NCH - 1; ++cc) { float* P = PL + (((size_t)chain * NCH + cc) * 2) * 4096; float* L = P + 4096 + i * 64;
;             float a0 = L[lane], a1 = 0.f, a2 = 0.f, a3 = 0.f;
; #pragma unroll
;             for (int k = 0; k < 64; k += 4) { a0 += __shfl(s, k) * P[k * 64 + lane]; a1 += __shfl(s, k + 1) * P[(k + 1) * 64 + lane]; a2 += __shfl(s, k + 2) * P[(k + 2) * 64 + lane]; a3 += __shfl(s, k + 3) * P[(k + 3) * 64 + lane]; }
;             s = (a0 + a1) + (a2 + a3); L[lane] = s; }
.LBB0_2032:
	s_waitcnt vmcnt(1)
	v_mov_b32_e32 v14, v12
	v_mov_b32_e32 v15, 0
	v_mov_b32_e32 v144, 0
	v_mov_b32_e32 v145, 0
	v_lshl_add_u64 v[168:169], v[6:7], 0, s[0:1]
	global_load_dword v13, v[168:169], off
	v_readlane_b32 s6, v159, 0
	v_readlane_b32 s7, v159, 1
	v_readlane_b32 vcc_lo, v159, 2
	v_readlane_b32 vcc_hi, v159, 3
	global_load_dword v80, v[160:161], off
	global_load_dword v81, v[160:161], off offset:256
	global_load_dword v82, v[160:161], off offset:512
	global_load_dword v83, v[160:161], off offset:768
	v_fmac_f32_e32 v14, s6, v16
	v_fmac_f32_e32 v15, s7, v17
	v_fmac_f32_e32 v144, vcc_lo, v18
	v_fmac_f32_e32 v145, vcc_hi, v19
	v_readlane_b32 s6, v159, 4
	v_readlane_b32 s7, v159, 5
	v_readlane_b32 vcc_lo, v159, 6
	v_readlane_b32 vcc_hi, v159, 7
	global_load_dword v84, v[160:161], off offset:1024
	global_load_dword v85, v[160:161], off offset:1280
	global_load_dword v86, v[160:161], off offset:1536
	global_load_dword v87, v[160:161], off offset:1792
	v_fmac_f32_e32 v14, s6, v20
	v_fmac_f32_e32 v15, s7, v21
	v_fmac_f32_e32 v144, vcc_lo, v22
	v_fmac_f32_e32 v145, vcc_hi, v23
	v_readlane_b32 s6, v159, 8
	v_readlane_b32 s7, v159, 9
	v_readlane_b32 vcc_lo, v159, 10
	v_readlane_b32 vcc_hi, v159, 11
	global_load_dword v88, v[160:161], off offset:2048
	global_load_dword v89, v[160:161], off offset:2304
	global_load_dword v90, v[160:161], off offset:2560
	global_load_dword v91, v[160:161], off offset:2816
	v_fmac_f32_e32 v14, s6, v24
	v_fmac_f32_e32 v15, s7, v25
	v_fmac_f32_e32 v144, vcc_lo, v26
	v_fmac_f32_e32 v145, vcc_hi, v27
	v_readlane_b32 s6, v159, 12
	v_readlane_b32 s7, v159, 13
	v_readlane_b32 vcc_lo, v159, 14
	v_readlane_b32 vcc_hi, v159, 15
	global_load_dword v92, v[160:161], off offset:3072
	global_load_dword v93, v[160:161], off offset:3328
	global_load_dword v94, v[160:161], off offset:3584
	global_load_dword v95, v[160:161], off offset:3840
	v_fmac_f32_e32 v14, s6, v28
	v_fmac_f32_e32 v15, s7, v29
	v_fmac_f32_e32 v144, vcc_lo, v30
	v_fmac_f32_e32 v145, vcc_hi, v31
	v_readlane_b32 s6, v159, 16
	v_readlane_b32 s7, v159, 17
	v_readlane_b32 vcc_lo, v159, 18
	v_readlane_b32 vcc_hi, v159, 19
	global_load_dword v96, v[162:163], off
	global_load_dword v97, v[162:163], off offset:256
	global_load_dword v98, v[162:163], off offset:512
	global_load_dword v99, v[162:163], off offset:768
	v_fmac_f32_e32 v14, s6, v32
	v_fmac_f32_e32 v15, s7, v33
	v_fmac_f32_e32 v144, vcc_lo, v34
	v_fmac_f32_e32 v145, vcc_hi, v35
	v_readlane_b32 s6, v159, 20
	v_readlane_b32 s7, v159, 21
	v_readlane_b32 vcc_lo, v159, 22
	v_readlane_b32 vcc_hi, v159, 23
	global_load_dword v100, v[162:163], off offset:1024
	global_load_dword v101, v[162:163], off offset:1280
	global_load_dword v102, v[162:163], off offset:1536
	global_load_dword v103, v[162:163], off offset:1792
	v_fmac_f32_e32 v14, s6, v36
	v_fmac_f32_e32 v15, s7, v37
	v_fmac_f32_e32 v144, vcc_lo, v38
	v_fmac_f32_e32 v145, vcc_hi, v39
	v_readlane_b32 s6, v159, 24
	v_readlane_b32 s7, v159, 25
	v_readlane_b32 vcc_lo, v159, 26
	v_readlane_b32 vcc_hi, v159, 27
	global_load_dword v104, v[162:163], off offset:2048
	global_load_dword v105, v[162:163], off offset:2304
	global_load_dword v106, v[162:163], off offset:2560
	global_load_dword v107, v[162:163], off offset:2816
	v_fmac_f32_e32 v14, s6, v40
	v_fmac_f32_e32 v15, s7, v41
	v_fmac_f32_e32 v144, vcc_lo, v42
	v_fmac_f32_e32 v145, vcc_hi, v43
	v_readlane_b32 s6, v159, 28
	v_readlane_b32 s7, v159, 29
	v_readlane_b32 vcc_lo, v159, 30
	v_readlane_b32 vcc_hi, v159, 31
	global_load_dword v108, v[162:163], off offset:3072
	global_load_dword v109, v[162:163], off offset:3328
	global_load_dword v110, v[162:163], off offset:3584
	global_load_dword v111, v[162:163], off offset:3840
	v_fmac_f32_e32 v14, s6, v44
	v_fmac_f32_e32 v15, s7, v45
	v_fmac_f32_e32 v144, vcc_lo, v46
	v_fmac_f32_e32 v145, vcc_hi, v47
	v_readlane_b32 s6, v159, 32
	v_readlane_b32 s7, v159, 33
	v_readlane_b32 vcc_lo, v159, 34
	v_readlane_b32 vcc_hi, v159, 35
	global_load_dword v112, v[164:165], off
	global_load_dword v113, v[164:165], off offset:256
	global_load_dword v114, v[164:165], off offset:512
	global_load_dword v115, v[164:165], off offset:768
	v_fmac_f32_e32 v14, s6, v48
	v_fmac_f32_e32 v15, s7, v49
	v_fmac_f32_e32 v144, vcc_lo, v50
	v_fmac_f32_e32 v145, vcc_hi, v51
	v_readlane_b32 s6, v159, 36
	v_readlane_b32 s7, v159, 37
	v_readlane_b32 vcc_lo, v159, 38
	v_readlane_b32 vcc_hi, v159, 39
	global_load_dword v116, v[164:165], off offset:1024
	global_load_dword v117, v[164:165], off offset:1280
	global_load_dword v118, v[164:165], off offset:1536
	global_load_dword v119, v[164:165], off offset:1792
	v_fmac_f32_e32 v14, s6, v52
	v_fmac_f32_e32 v15, s7, v53
	v_fmac_f32_e32 v144, vcc_lo, v54
	v_fmac_f32_e32 v145, vcc_hi, v55
	v_readlane_b32 s6, v159, 40
	v_readlane_b32 s7, v159, 41
	v_readlane_b32 vcc_lo, v159, 42
	v_readlane_b32 vcc_hi, v159, 43
	global_load_dword v120, v[164:165], off offset:2048
	global_load_dword v121, v[164:165], off offset:2304
	global_load_dword v122, v[164:165], off offset:2560
	global_load_dword v123, v[164:165], off offset:2816
	v_fmac_f32_e32 v14, s6, v56
	v_fmac_f32_e32 v15, s7, v57
	v_fmac_f32_e32 v144, vcc_lo, v58
	v_fmac_f32_e32 v145, vcc_hi, v59
	v_readlane_b32 s6, v159, 44
	v_readlane_b32 s7, v159, 45
	v_readlane_b32 vcc_lo, v159, 46
	v_readlane_b32 vcc_hi, v159, 47
	global_load_dword v124, v[164:165], off offset:3072
	global_load_dword v125, v[164:165], off offset:3328
	global_load_dword v126, v[164:165], off offset:3584
	global_load_dword v127, v[164:165], off offset:3840
	v_fmac_f32_e32 v14, s6, v60
	v_fmac_f32_e32 v15, s7, v61
	v_fmac_f32_e32 v144, vcc_lo, v62
; __device__ __forceinline__ void scan_pass2(const Ctx&, unsigned char* ws) { const Ctx c = mk_ctx();
;     ...
;         for (int cc = 0; cc < NCH - 1; ++cc) { float* P = PL + (((size_t)chain * NCH + cc) * 2) * 4096; float* L = P + 4096 + i * 64;
;             float a0 = L[lane], a1 = 0.f, a2 = 0.f, a3 = 0.f;
; #pragma unroll
;             for (int k = 0; k < 64; k += 4) { a0 += __shfl(s, k) * P[k * 64 + lane]; a1 += __shfl(s, k + 1) * P[(k + 1) * 64 + lane]; a2 += __shfl(s, k + 2) * P[(k + 2) * 64 + lane]; a3 += __shfl(s, k + 3) * P[(k + 3) * 64 + lane]; }
;             s = (a0 + a1) + (a2 + a3); L[lane] = s; }
	v_fmac_f32_e32 v145, vcc_hi, v63
	v_readlane_b32 s6, v159, 48
	v_readlane_b32 s7, v159, 49
	v_readlane_b32 vcc_lo, v159, 50
	v_readlane_b32 vcc_hi, v159, 51
	global_load_dword v128, v[166:167], off
	global_load_dword v129, v[166:167], off offset:256
	global_load_dword v130, v[166:167], off offset:512
	global_load_dword v131, v[166:167], off offset:768
	v_fmac_f32_e32 v14, s6, v64
	v_fmac_f32_e32 v15, s7, v65
	v_fmac_f32_e32 v144, vcc_lo, v66
	v_fmac_f32_e32 v145, vcc_hi, v67
	v_readlane_b32 s6, v159, 52
	v_readlane_b32 s7, v159, 53
	v_readlane_b32 vcc_lo, v159, 54
	v_readlane_b32 vcc_hi, v159, 55
	global_load_dword v132, v[166:167], off offset:1024
	global_load_dword v133, v[166:167], off offset:1280
	global_load_dword v134, v[166:167], off offset:1536
	global_load_dword v135, v[166:167], off offset:1792
	v_fmac_f32_e32 v14, s6, v68
	v_fmac_f32_e32 v15, s7, v69
	v_fmac_f32_e32 v144, vcc_lo, v70
	v_fmac_f32_e32 v145, vcc_hi, v71
	v_readlane_b32 s6, v159, 56
	v_readlane_b32 s7, v159, 57
	v_readlane_b32 vcc_lo, v159, 58
	v_readlane_b32 vcc_hi, v159, 59
	global_load_dword v136, v[166:167], off offset:2048
	global_load_dword v137, v[166:167], off offset:2304
	global_load_dword v138, v[166:167], off offset:2560
	global_load_dword v139, v[166:167], off offset:2816
	v_fmac_f32_e32 v14, s6, v72
	v_fmac_f32_e32 v15, s7, v73
	v_fmac_f32_e32 v144, vcc_lo, v74
	v_fmac_f32_e32 v145, vcc_hi, v75
	v_readlane_b32 s6, v159, 60
	v_readlane_b32 s7, v159, 61
	v_readlane_b32 vcc_lo, v159, 62
	v_readlane_b32 vcc_hi, v159, 63
	global_load_dword v140, v[166:167], off offset:3072
	global_load_dword v141, v[166:167], off offset:3328
	global_load_dword v142, v[166:167], off offset:3584
	global_load_dword v143, v[166:167], off offset:3840
	v_fmac_f32_e32 v14, s6, v76
	v_fmac_f32_e32 v15, s7, v77
	v_fmac_f32_e32 v144, vcc_lo, v78
	v_fmac_f32_e32 v145, vcc_hi, v79
	v_add_f32_e32 v14, v14, v15
	v_add_f32_e32 v144, v144, v145
	v_add_u32_e32 v170, 1, v170
	v_add_f32_e32 v159, v144, v14
	v_readfirstlane_b32 s6, v170
	global_store_dword v[6:7], v159, off
	v_mov_b32_e32 v6, v168
	v_mov_b32_e32 v7, v169
	v_lshl_add_u64 v[160:161], v[160:161], 0, s[0:1]
	v_lshl_add_u64 v[162:163], v[162:163], 0, s[0:1]
	v_lshl_add_u64 v[164:165], v[164:165], 0, s[0:1]
	v_lshl_add_u64 v[166:167], v[166:167], 0, s[0:1]
	s_cmp_eq_u32 s6, 63
	s_cbranch_scc1 .Ls2_done
	s_waitcnt vmcnt(1)
	v_mov_b32_e32 v14, v13
	v_mov_b32_e32 v15, 0
	v_mov_b32_e32 v144, 0
	v_mov_b32_e32 v145, 0
	v_lshl_add_u64 v[168:169], v[6:7], 0, s[0:1]
	global_load_dword v12, v[168:169], off
	v_readlane_b32 s6, v159, 0
	v_readlane_b32 s7, v159, 1
	v_readlane_b32 vcc_lo, v159, 2
	v_readlane_b32 vcc_hi, v159, 3
	global_load_dword v16, v[160:161], off
	global_load_dword v17, v[160:161], off offset:256
	global_load_dword v18, v[160:161], off offset:512
	global_load_dword v19, v[160:161], off offset:768
	v_fmac_f32_e32 v14, s6, v80
	v_fmac_f32_e32 v15, s7, v81
	v_fmac_f32_e32 v144, vcc_lo, v82
	v_fmac_f32_e32 v145, vcc_hi, v83
	v_readlane_b32 s6, v159, 4
	v_readlane_b32 s7, v159, 5
	v_readlane_b32 vcc_lo, v159, 6
	v_readlane_b32 vcc_hi, v159, 7
	global_load_dword v20, v[160:161], off offset:1024
	global_load_dword v21, v[160:161], off offset:1280
	global_load_dword v22, v[160:161], off offset:1536
	global_load_dword v23, v[160:161], off offset:1792
	v_fmac_f32_e32 v14, s6, v84
	v_fmac_f32_e32 v15, s7, v85
	v_fmac_f32_e32 v144, vcc_lo, v86
	v_fmac_f32_e32 v145, vcc_hi, v87
	v_readlane_b32 s6, v159, 8
	v_readlane_b32 s7, v159, 9
	v_readlane_b32 vcc_lo, v159, 10
	v_readlane_b32 vcc_hi, v159, 11
	global_load_dword v24, v[160:161], off offset:2048
	global_load_dword v25, v[160:161], off offset:2304
	global_load_dword v26, v[160:161], off offset:2560
	global_load_dword v27, v[160:161], off offset:2816
	v_fmac_f32_e32 v14, s6, v88
	v_fmac_f32_e32 v15, s7, v89
	v_fmac_f32_e32 v144, vcc_lo, v90
	v_fmac_f32_e32 v145, vcc_hi, v91
	v_readlane_b32 s6, v159, 12
	v_readlane_b32 s7, v159, 13
	v_readlane_b32 vcc_lo, v159, 14
	v_readlane_b32 vcc_hi, v159, 15
	global_load_dword v28, v[160:161], off offset:3072
	global_load_dword v29, v[160:161], off offset:3328
	global_load_dword v30, v[160:161], off offset:3584
	global_load_dword v31, v[160:161], off offset:3840
	v_fmac_f32_e32 v14, s6, v92
	v_fmac_f32_e32 v15, s7, v93
	v_fmac_f32_e32 v144, vcc_lo, v94
	v_fmac_f32_e32 v145, vcc_hi, v95
	v_readlane_b32 s6, v159, 16
	v_readlane_b32 s7, v159, 17
	v_readlane_b32 vcc_lo, v159, 18
	v_readlane_b32 vcc_hi, v159, 19
	global_load_dword v32, v[162:163], off
	global_load_dword v33, v[162:163], off offset:256
	global_load_dword v34, v[162:163], off offset:512
	global_load_dword v35, v[162:163], off offset:768
	v_fmac_f32_e32 v14, s6, v96
	v_fmac_f32_e32 v15, s7, v97
	v_fmac_f32_e32 v144, vcc_lo, v98
	v_fmac_f32_e32 v145, vcc_hi, v99
	v_readlane_b32 s6, v159, 20
	v_readlane_b32 s7, v159, 21
	v_readlane_b32 vcc_lo, v159, 22
	v_readlane_b32 vcc_hi, v159, 23
	global_load_dword v36, v[162:163], off offset:1024
	global_load_dword v37, v[162:163], off offset:1280
	global_load_dword v38, v[162:163], off offset:1536
	global_load_dword v39, v[162:163], off offset:1792
	v_fmac_f32_e32 v14, s6, v100
	v_fmac_f32_e32 v15, s7, v101
	v_fmac_f32_e32 v144, vcc_lo, v102
	v_fmac_f32_e32 v145, vcc_hi, v103
; __device__ __forceinline__ void scan_pass2(const Ctx&, unsigned char* ws) { const Ctx c = mk_ctx();
;     ...
;     for (int task = (gridDim.x == 256) ? ((tt_ < 128) ? ((xcd_ + 8 * (tt_ >> 6)) * 64 + (tt_ & 63)) : 16 * 64) : c.gw; task < 16 * 64; task += (gridDim.x == 256) ? 16 * 64 : c.NGW) { const int chain = task >> 6, i = task & 63;
;         float s = 0.f;
;         for (int cc = 0; cc < NCH - 1; ++cc) { float* P = PL + (((size_t)chain * NCH + cc) * 2) * 4096; float* L = P + 4096 + i * 64;
;             float a0 = L[lane], a1 = 0.f, a2 = 0.f, a3 = 0.f;
; #pragma unroll
;             for (int k = 0; k < 64; k += 4) { a0 += __shfl(s, k) * P[k * 64 + lane]; a1 += __shfl(s, k + 1) * P[(k + 1) * 64 + lane]; a2 += __shfl(s, k + 2) * P[(k + 2) * 64 + lane]; a3 += __shfl(s, k + 3) * P[(k + 3) * 64 + lane]; }
;             s = (a0 + a1) + (a2 + a3); L[lane] = s; }
;     }
	v_readlane_b32 s6, v159, 24
	v_readlane_b32 s7, v159, 25
	v_readlane_b32 vcc_lo, v159, 26
	v_readlane_b32 vcc_hi, v159, 27
	global_load_dword v40, v[162:163], off offset:2048
	global_load_dword v41, v[162:163], off offset:2304
	global_load_dword v42, v[162:163], off offset:2560
	global_load_dword v43, v[162:163], off offset:2816
	v_fmac_f32_e32 v14, s6, v104
	v_fmac_f32_e32 v15, s7, v105
	v_fmac_f32_e32 v144, vcc_lo, v106
	v_fmac_f32_e32 v145, vcc_hi, v107
	v_readlane_b32 s6, v159, 28
	v_readlane_b32 s7, v159, 29
	v_readlane_b32 vcc_lo, v159, 30
	v_readlane_b32 vcc_hi, v159, 31
	global_load_dword v44, v[162:163], off offset:3072
	global_load_dword v45, v[162:163], off offset:3328
	global_load_dword v46, v[162:163], off offset:3584
	global_load_dword v47, v[162:163], off offset:3840
	v_fmac_f32_e32 v14, s6, v108
	v_fmac_f32_e32 v15, s7, v109
	v_fmac_f32_e32 v144, vcc_lo, v110
	v_fmac_f32_e32 v145, vcc_hi, v111
	v_readlane_b32 s6, v159, 32
	v_readlane_b32 s7, v159, 33
	v_readlane_b32 vcc_lo, v159, 34
	v_readlane_b32 vcc_hi, v159, 35
	global_load_dword v48, v[164:165], off
	global_load_dword v49, v[164:165], off offset:256
	global_load_dword v50, v[164:165], off offset:512
	global_load_dword v51, v[164:165], off offset:768
	v_fmac_f32_e32 v14, s6, v112
	v_fmac_f32_e32 v15, s7, v113
	v_fmac_f32_e32 v144, vcc_lo, v114
	v_fmac_f32_e32 v145, vcc_hi, v115
	v_readlane_b32 s6, v159, 36
	v_readlane_b32 s7, v159, 37
	v_readlane_b32 vcc_lo, v159, 38
	v_readlane_b32 vcc_hi, v159, 39
	global_load_dword v52, v[164:165], off offset:1024
	global_load_dword v53, v[164:165], off offset:1280
	global_load_dword v54, v[164:165], off offset:1536
	global_load_dword v55, v[164:165], off offset:1792
	v_fmac_f32_e32 v14, s6, v116
	v_fmac_f32_e32 v15, s7, v117
	v_fmac_f32_e32 v144, vcc_lo, v118
	v_fmac_f32_e32 v145, vcc_hi, v119
	v_readlane_b32 s6, v159, 40
	v_readlane_b32 s7, v159, 41
	v_readlane_b32 vcc_lo, v159, 42
	v_readlane_b32 vcc_hi, v159, 43
	global_load_dword v56, v[164:165], off offset:2048
	global_load_dword v57, v[164:165], off offset:2304
	global_load_dword v58, v[164:165], off offset:2560
	global_load_dword v59, v[164:165], off offset:2816
	v_fmac_f32_e32 v14, s6, v120
	v_fmac_f32_e32 v15, s7, v121
	v_fmac_f32_e32 v144, vcc_lo, v122
	v_fmac_f32_e32 v145, vcc_hi, v123
	v_readlane_b32 s6, v159, 44
	v_readlane_b32 s7, v159, 45
	v_readlane_b32 vcc_lo, v159, 46
	v_readlane_b32 vcc_hi, v159, 47
	global_load_dword v60, v[164:165], off offset:3072
	global_load_dword v61, v[164:165], off offset:3328
	global_load_dword v62, v[164:165], off offset:3584
	global_load_dword v63, v[164:165], off offset:3840
	v_fmac_f32_e32 v14, s6, v124
	v_fmac_f32_e32 v15, s7, v125
	v_fmac_f32_e32 v144, vcc_lo, v126
	v_fmac_f32_e32 v145, vcc_hi, v127
	v_readlane_b32 s6, v159, 48
	v_readlane_b32 s7, v159, 49
	v_readlane_b32 vcc_lo, v159, 50
	v_readlane_b32 vcc_hi, v159, 51
	global_load_dword v64, v[166:167], off
	global_load_dword v65, v[166:167], off offset:256
	global_load_dword v66, v[166:167], off offset:512
	global_load_dword v67, v[166:167], off offset:768
	v_fmac_f32_e32 v14, s6, v128
	v_fmac_f32_e32 v15, s7, v129
	v_fmac_f32_e32 v144, vcc_lo, v130
	v_fmac_f32_e32 v145, vcc_hi, v131
	v_readlane_b32 s6, v159, 52
	v_readlane_b32 s7, v159, 53
	v_readlane_b32 vcc_lo, v159, 54
	v_readlane_b32 vcc_hi, v159, 55
	global_load_dword v68, v[166:167], off offset:1024
	global_load_dword v69, v[166:167], off offset:1280
	global_load_dword v70, v[166:167], off offset:1536
	global_load_dword v71, v[166:167], off offset:1792
	v_fmac_f32_e32 v14, s6, v132
	v_fmac_f32_e32 v15, s7, v133
	v_fmac_f32_e32 v144, vcc_lo, v134
	v_fmac_f32_e32 v145, vcc_hi, v135
	v_readlane_b32 s6, v159, 56
	v_readlane_b32 s7, v159, 57
	v_readlane_b32 vcc_lo, v159, 58
	v_readlane_b32 vcc_hi, v159, 59
	global_load_dword v72, v[166:167], off offset:2048
	global_load_dword v73, v[166:167], off offset:2304
	global_load_dword v74, v[166:167], off offset:2560
	global_load_dword v75, v[166:167], off offset:2816
	v_fmac_f32_e32 v14, s6, v136
	v_fmac_f32_e32 v15, s7, v137
	v_fmac_f32_e32 v144, vcc_lo, v138
	v_fmac_f32_e32 v145, vcc_hi, v139
	v_readlane_b32 s6, v159, 60
	v_readlane_b32 s7, v159, 61
	v_readlane_b32 vcc_lo, v159, 62
	v_readlane_b32 vcc_hi, v159, 63
	global_load_dword v76, v[166:167], off offset:3072
	global_load_dword v77, v[166:167], off offset:3328
	global_load_dword v78, v[166:167], off offset:3584
	global_load_dword v79, v[166:167], off offset:3840
	v_fmac_f32_e32 v14, s6, v140
	v_fmac_f32_e32 v15, s7, v141
	v_fmac_f32_e32 v144, vcc_lo, v142
	v_fmac_f32_e32 v145, vcc_hi, v143
	v_add_f32_e32 v14, v14, v15
	v_add_f32_e32 v144, v144, v145
	v_add_u32_e32 v170, 1, v170
	v_add_f32_e32 v159, v144, v14
	v_readfirstlane_b32 s6, v170
	global_store_dword v[6:7], v159, off
	v_mov_b32_e32 v6, v168
	v_mov_b32_e32 v7, v169
	v_lshl_add_u64 v[160:161], v[160:161], 0, s[0:1]
	v_lshl_add_u64 v[162:163], v[162:163], 0, s[0:1]
	v_lshl_add_u64 v[164:165], v[164:165], 0, s[0:1]
	v_lshl_add_u64 v[166:167], v[166:167], 0, s[0:1]
	s_cmp_eq_u32 s6, 63
	s_cbranch_scc1 .Ls2_done
	s_branch .LBB0_2032
.Ls2_done:
	s_waitcnt vmcnt(0)
	v_readlane_b32 s0, v254, 46
	s_add_i32 s4, s4, s0
	v_readlane_b32 s0, v254, 47
	s_add_i32 s5, s5, s0
	s_cmpk_gt_i32 s4, 0x3ff
	s_cbranch_scc0 .LBB0_2031
